# forgetting-attention phase: static s_setprio 1 for waves 0-3 for the whole key loop, on top of v066
# baseline (speedup 1.0000x reference)
; #define BID opqs((int)blockIdx.x)
; DI float shflx(float v, int m, int lane) { return __int_as_float(__builtin_amdgcn_ds_bpermute((lane ^ m) << 2, __float_as_int(v))); }
; template <int MODE>
; DI void attn_item(const u16* Qp, int ldq, const u16* Kp, int ldk, const u16* VTp, int ldv, u16* Op, int ldo,
;                   int q0, int nkt, const float* Fc, const unsigned* BM, float kmaxn, char* smem) {
;     ...
;   const float l = l_run + shflx(l_run, 32, lane);
;   const float inv = 1.f / l;
;   u16* orow = Op + (size_t)q * ldo;
; #pragma unroll
;   for (int dt = 0; dt < 4; ++dt)
; #pragma unroll
;     for (int j = 0; j < 4; ++j) {
;       uint2 u; u.x = pk2(o[dt][j * 4 + 0] * inv, o[dt][j * 4 + 1] * inv); u.y = pk2(o[dt][j * 4 + 2] * inv, o[dt][j * 4 + 3] * inv);
;       *(uint2*)(orow + 32 * dt + 8 * j + 4 * h) = u;
;     }
; }
; template <int MODE>
; DI void self_attn_phase(const Params& p, int qcol, int kcol, int j, char* smem) {
;   const u16* H = (const u16*)(p.ws + O_H); const u16* VT = (const u16*)(p.ws + O_VT); u16* CAT = (u16*)(p.ws + O_CAT);
;   const float* FC = (const float*)(p.ws + O_FC); const unsigned* BM = (const unsigned*)(p.ws + O_BM);
;   for (int idx = BID; idx < 512; idx += gridDim.x) {
;     const int bh = idx & 15, qi = idx >> 4;
;     const int qb = (qi < 16) ? (31 - qi) : (qi - 16);
;     const int b = bh >> 3, hd = bh & 7;
;     const int q0 = qb * 256, nkt = 4 * (qb + 1);
;     attn_item<MODE>(H + (size_t)b * S_ * HLD + qcol + hd * 128, HLD, H + (size_t)b * S_ * HLD + kcol + hd * 128, HLD,
;                     VT + ((size_t)b * 1024 + hd * 128) * S_, S_, CAT + (size_t)b * S_ * DM + 1024 + hd * 128, DM,
;                     q0, nkt, FC + (size_t)(b * 8 + hd) * S_, BM + (size_t)b * S_ * 256,
;                     (MODE == 1) ? sqrtf(__uint_as_float(((const unsigned*)(p.ws + O_BAR))[KN_WORD0 + j * 8 + hd])) : 0.f, smem);
;   }
.LBB0_465:
	s_cmp_lt_i32 s62, 2
	s_mov_b64 s[6:7], -1
	s_cbranch_scc1 .LBB0_895
	s_cmp_lt_i32 s62, 3
	s_cbranch_scc1 .LBB0_815
	s_cmp_gt_i32 s62, 3
	s_cbranch_scc0 .LBB0_497
	s_add_u32 s40, s90, 0x26b00000
	s_addc_u32 s41, s91, 0
	s_add_u32 s42, s90, 0x31300000
	s_addc_u32 s43, s91, 0
	s_and_b64 vcc, exec, s[56:57]
	s_cbranch_vccz .LBB0_485
	v_readlane_b32 s36, v254, 0
	s_cmpk_gt_i32 s36, 0x1ff
	s_cbranch_scc1 .LBB0_484
	s_add_u32 s44, s90, 0x39400000
	s_addc_u32 s45, s91, 0
	s_lshl_b32 s46, s58, 3
	s_addk_i32 s46, 0x1f40
	s_add_u32 s47, s90, 0x4f480000
	s_addc_u32 s48, s91, 0
	v_readfirstlane_b32 s7, v201
	s_nop 3
	s_lshr_b32 s7, s7, 8
	s_cmp_eq_u32 s7, 1
	s_cbranch_scc1 .Lpriofox_done
	s_setprio 1
.Lpriofox_done:
	s_branch .LBB0_472
.LBB0_471:
	ds_bpermute_b32 v66, v143, v161
	s_lshl_b32 s6, s50, 25
	s_add_u32 s6, s90, s6
	s_addc_u32 s7, s91, 0
	s_lshl_b32 s8, s49, 1
	s_waitcnt lgkmcnt(0)
	v_add_f32_e32 v66, v161, v66
	s_add_u32 s6, s6, s8
	v_div_scale_f32 v67, s[8:9], v66, v66, 1.0
	v_rcp_f32_e32 v68, v67
	s_addc_u32 s7, s7, 0
	s_waitcnt vmcnt(0)
	v_fma_f32 v69, -v67, v68, 1.0
	v_fmac_f32_e32 v68, v69, v68
	v_div_scale_f32 v69, vcc, 1.0, v66, 1.0
	v_mul_f32_e32 v70, v69, v68
	v_fma_f32 v71, -v67, v70, v69
	v_fmac_f32_e32 v70, v71, v68
	v_fma_f32 v67, -v67, v70, v69
	v_div_fmas_f32 v67, v67, v68, v70
	v_lshlrev_b64 v[68:69], 12, v[134:135]
	v_lshl_add_u64 v[68:69], s[6:7], 0, v[68:69]
	v_div_fixup_f32 v66, v67, v66, 1.0
	v_lshl_add_u64 v[68:69], v[68:69], 0, v[0:1]
	s_mov_b64 s[6:7], 0x33300800
	v_lshl_add_u64 v[70:71], v[68:69], 0, s[6:7]
	v_pk_mul_f32 v[50:51], v[50:51], v[66:67] op_sel_hi:[1,0]
	v_pk_mul_f32 v[52:53], v[52:53], v[66:67] op_sel_hi:[1,0]
	s_mov_b32 s6, 0x33300000
	v_cvt_pk_bf16_f32 v50, v50, v51
	v_cvt_pk_bf16_f32 v51, v52, v53
	v_add_co_u32_e32 v52, vcc, s6, v68
	v_pk_mul_f32 v[34:35], v[34:35], v[66:67] op_sel_hi:[1,0]
	v_pk_mul_f32 v[36:37], v[36:37], v[66:67] op_sel_hi:[1,0]
	v_pk_mul_f32 v[18:19], v[18:19], v[66:67] op_sel_hi:[1,0]
	v_pk_mul_f32 v[20:21], v[20:21], v[66:67] op_sel_hi:[1,0]
	v_pk_mul_f32 v[2:3], v[2:3], v[66:67] op_sel_hi:[1,0]
	v_pk_mul_f32 v[4:5], v[4:5], v[66:67] op_sel_hi:[1,0]
	v_addc_co_u32_e32 v53, vcc, 0, v69, vcc
	v_cvt_pk_bf16_f32 v34, v34, v35
	v_cvt_pk_bf16_f32 v35, v36, v37
	v_cvt_pk_bf16_f32 v18, v18, v19
	v_cvt_pk_bf16_f32 v19, v20, v21
	v_cvt_pk_bf16_f32 v2, v2, v3
	v_cvt_pk_bf16_f32 v3, v4, v5
	s_barrier
	global_store_dwordx2 v[52:53], v[50:51], off offset:2048
	v_pk_mul_f32 v[50:51], v[54:55], v[66:67] op_sel_hi:[1,0]
	v_pk_mul_f32 v[52:53], v[56:57], v[66:67] op_sel_hi:[1,0]
	global_store_dwordx2 v[70:71], v[34:35], off offset:64
	v_pk_mul_f32 v[34:35], v[38:39], v[66:67] op_sel_hi:[1,0]
	v_pk_mul_f32 v[36:37], v[40:41], v[66:67] op_sel_hi:[1,0]
	global_store_dwordx2 v[70:71], v[18:19], off offset:128
	v_pk_mul_f32 v[18:19], v[22:23], v[66:67] op_sel_hi:[1,0]
	v_pk_mul_f32 v[20:21], v[24:25], v[66:67] op_sel_hi:[1,0]
	global_store_dwordx2 v[70:71], v[2:3], off offset:192
	v_pk_mul_f32 v[2:3], v[6:7], v[66:67] op_sel_hi:[1,0]
	v_pk_mul_f32 v[4:5], v[8:9], v[66:67] op_sel_hi:[1,0]
	v_cvt_pk_bf16_f32 v50, v50, v51
	v_cvt_pk_bf16_f32 v51, v52, v53
	v_cvt_pk_bf16_f32 v34, v34, v35
	v_cvt_pk_bf16_f32 v35, v36, v37
	v_cvt_pk_bf16_f32 v18, v18, v19
	v_cvt_pk_bf16_f32 v19, v20, v21
	v_cvt_pk_bf16_f32 v2, v2, v3
	v_cvt_pk_bf16_f32 v3, v4, v5
	global_store_dwordx2 v[70:71], v[50:51], off offset:16
	v_pk_mul_f32 v[50:51], v[58:59], v[66:67] op_sel_hi:[1,0]
	v_pk_mul_f32 v[52:53], v[60:61], v[66:67] op_sel_hi:[1,0]
	global_store_dwordx2 v[70:71], v[34:35], off offset:80
	v_pk_mul_f32 v[34:35], v[42:43], v[66:67] op_sel_hi:[1,0]
	v_pk_mul_f32 v[36:37], v[44:45], v[66:67] op_sel_hi:[1,0]
	global_store_dwordx2 v[70:71], v[18:19], off offset:144
	v_pk_mul_f32 v[18:19], v[26:27], v[66:67] op_sel_hi:[1,0]
	v_pk_mul_f32 v[20:21], v[28:29], v[66:67] op_sel_hi:[1,0]
	global_store_dwordx2 v[70:71], v[2:3], off offset:208
	v_pk_mul_f32 v[2:3], v[10:11], v[66:67] op_sel_hi:[1,0]
	v_pk_mul_f32 v[4:5], v[12:13], v[66:67] op_sel_hi:[1,0]
	v_cvt_pk_bf16_f32 v50, v50, v51
	v_cvt_pk_bf16_f32 v51, v52, v53
	v_cvt_pk_bf16_f32 v34, v34, v35
	v_cvt_pk_bf16_f32 v35, v36, v37
	v_cvt_pk_bf16_f32 v18, v18, v19
	v_cvt_pk_bf16_f32 v19, v20, v21
	v_cvt_pk_bf16_f32 v2, v2, v3
	v_cvt_pk_bf16_f32 v3, v4, v5
	v_readlane_b32 s6, v254, 1
	global_store_dwordx2 v[70:71], v[50:51], off offset:32
	v_pk_mul_f32 v[50:51], v[62:63], v[66:67] op_sel_hi:[1,0]
	v_pk_mul_f32 v[52:53], v[64:65], v[66:67] op_sel_hi:[1,0]
	global_store_dwordx2 v[70:71], v[34:35], off offset:96
	v_pk_mul_f32 v[34:35], v[46:47], v[66:67] op_sel_hi:[1,0]
	v_pk_mul_f32 v[36:37], v[48:49], v[66:67] op_sel_hi:[1,0]
	global_store_dwordx2 v[70:71], v[18:19], off offset:160
	v_pk_mul_f32 v[18:19], v[30:31], v[66:67] op_sel_hi:[1,0]
	v_pk_mul_f32 v[20:21], v[32:33], v[66:67] op_sel_hi:[1,0]
	global_store_dwordx2 v[70:71], v[2:3], off offset:224
	v_pk_mul_f32 v[2:3], v[14:15], v[66:67] op_sel_hi:[1,0]
	v_pk_mul_f32 v[4:5], v[16:17], v[66:67] op_sel_hi:[1,0]
	s_add_i32 s36, s36, s6
	v_cvt_pk_bf16_f32 v50, v50, v51
	v_cvt_pk_bf16_f32 v51, v52, v53
	v_cvt_pk_bf16_f32 v34, v34, v35
	v_cvt_pk_bf16_f32 v35, v36, v37
	v_cvt_pk_bf16_f32 v18, v18, v19
	v_cvt_pk_bf16_f32 v19, v20, v21
	v_cvt_pk_bf16_f32 v2, v2, v3
	v_cvt_pk_bf16_f32 v3, v4, v5
	s_cmpk_gt_i32 s36, 0x1ff
	global_store_dwordx2 v[70:71], v[50:51], off offset:48
	global_store_dwordx2 v[70:71], v[34:35], off offset:112
	global_store_dwordx2 v[70:71], v[18:19], off offset:176
	v_readlane_b32 s7, v254, 2
	global_store_dwordx2 v[70:71], v[2:3], off offset:240
	s_cbranch_scc1 .LBB0_484
